# rstd table built by waves 0-3 only (waves 4-7 no longer duplicate the 16 partial-sum loads at phase start)
# speedup vs baseline: 1.0085x; 1.0085x over previous
; #define PG8_WAIT_V(n) asm volatile("s_waitcnt vmcnt(" #n ")" ::: "memory")
; #define PG8_BAR __builtin_amdgcn_s_barrier()
; __device__ __forceinline__ void epi_rstd(const float* ssq, int row0, int fq, float (&rs)[2][4]) {
;     float part[2][4][4];
; #pragma unroll
;     for (int ai = 0; ai < 2; ++ai)
; #pragma unroll
;         for (int m = 0; m < 4; ++m)
; #pragma unroll
;             for (int j = 0; j < 4; ++j) part[ai][m][j] = ssq[(size_t)(4 * fq + j) * M + row0 + ai * 128 + m * 16];
; #pragma unroll
;     for (int ai = 0; ai < 2; ++ai)
; #pragma unroll
;         for (int m = 0; m < 4; ++m) { float t = (part[ai][m][0] + part[ai][m][1]) + (part[ai][m][2] + part[ai][m][3]); t += __shfl_xor(t, 16); t += __shfl_xor(t, 32); rs[ai][m] = __builtin_amdgcn_rsqf(t * (1.0f / 1024.0f) + EPS); }
; __device__ __forceinline__ void gemm_phase(LAS unsigned char* lds, const Sched& S, const Epi& E) {
;     ...
;     const int tid = tid_, wid = __builtin_amdgcn_readfirstlane(tid >> 6), lane = tid & 63, wr = wid >> 2, wc = wid & 3, fr = lane & 15, fq = lane >> 4;
;     int R0, C0, R1, C1; stage_rc(tid * 16, R0, C0); stage_rc(tid * 16 + 8192, R1, C1);
;     const int Rb0 = (R0 & ~31) + perm32(R0 & 31), Rb1 = (R1 & ~31) + perm32(R1 & 31);
;     const size_t kstep = (size_t)(BK * 2);
;     const unsigned ldsw = (unsigned)wid * 1024u;
;     const int aoff = lds_byte(wr * 64 + fr, fq * 8), boff = lds_byte(wc * 32 + fr, fq * 8);
;     ...
;     Unit cur, nxt; int ui = 0;
;     if (!S.next(0, cur)) return;
;     f32x4 acc[2][2][4][2];
; #pragma unroll
;     for (int a = 0; a < 2; ++a)
; #pragma unroll
;         for (int b = 0; b < 2; ++b)
; #pragma unroll
;             for (int m = 0; m < 4; ++m)
; #pragma unroll
;                 for (int n = 0; n < 2; ++n) acc[a][b][m][n] = (f32x4){0.f, 0.f, 0.f, 0.f};
;     bf16x8 At[4][2], B0[2][2], B1[2][2];
;     const char* cA = cur.a; const char* cB = cur.b;
;     const unsigned RA0 = R0 * 2, RA1 = R1 * 2, RB0 = Rb0 * 2, RB1 = Rb1 * 2, CC0 = C0 * 2, CC1 = C1 * 2;
;     ...
;     int lda = cur.lda, ldb = cur.ldb;
;     { const size_t hA = (size_t)HALF * lda * 2, hB = (size_t)HALF * ldb * 2;
;     PG8_STB(PG8_SB(0, 0), cB, ldb); PG8_STB(PG8_SB(0, 1), cB + hB, ldb); PG8_STA(PG8_SA(0, 0), cA, lda); PG8_STA(PG8_SA(0, 1), cA + hA, lda);
;     if (wr == 1) PG8_BAR;
;     PG8_WAIT_V(2); PG8_BAR;
.LBB0_256:
	v_readlane_b32 s12, v250, 13
	s_mov_b32 s13, -1
	s_cmp_eq_u32 s12, 0
	s_cbranch_scc1 .Lmy_tab_yes
	s_cmp_eq_u32 s12, 5
	s_cbranch_scc1 .Lmy_tab_yes
	v_writelane_b32 v250, s13, 41
	s_mov_b32 s12, 0
	s_nop 0
	v_writelane_b32 v250, s12, 42
	s_branch .Lmy_tab_done
.Lmy_tab_yes:
	v_writelane_b32 v250, s95, 41
	v_readfirstlane_b32 s12, v195
	s_nop 0
	s_lshr_b32 s12, s12, 8
	s_cmp_lg_u32 s12, 0
	s_cbranch_scc0 .Lmy_tab_ld
	s_mov_b32 s12, 0
	s_nop 0
	v_writelane_b32 v250, s12, 42
	s_branch .Lmy_tab_done
	s_nop 0
	s_nop 0
	s_nop 0
	s_nop 0
	s_nop 0
	s_nop 0
	s_nop 0
	s_nop 0
	s_nop 0
	s_nop 0
	s_nop 0
	s_nop 0
	s_nop 0
	s_nop 0
.Lmy_tab_ld:
	s_mov_b32 s12, 1
	s_nop 0
	v_writelane_b32 v250, s12, 42
	v_readlane_b32 s12, v250, 3
	v_readlane_b32 s13, v250, 4
	v_and_b32_e32 v64, 0xff, v195
	v_lshl_add_u32 v64, s95, 8, v64
	v_lshlrev_b32_e32 v64, 2, v64
	s_nop 3
	global_load_dword v66, v64, s[12:13]
	v_add_u32_e32 v65, 0x10000, v64
	global_load_dword v67, v65, s[12:13]
	v_add_u32_e32 v65, 0x20000, v64
	global_load_dword v68, v65, s[12:13]
	v_add_u32_e32 v65, 0x30000, v64
	global_load_dword v69, v65, s[12:13]
	v_add_u32_e32 v65, 0x40000, v64
	global_load_dword v70, v65, s[12:13]
	v_add_u32_e32 v65, 0x50000, v64
	global_load_dword v71, v65, s[12:13]
	v_add_u32_e32 v65, 0x60000, v64
	global_load_dword v72, v65, s[12:13]
	v_add_u32_e32 v65, 0x70000, v64
	global_load_dword v73, v65, s[12:13]
	v_add_u32_e32 v65, 0x80000, v64
	global_load_dword v74, v65, s[12:13]
	v_add_u32_e32 v65, 0x90000, v64
	global_load_dword v75, v65, s[12:13]
	v_add_u32_e32 v65, 0xa0000, v64
	global_load_dword v76, v65, s[12:13]
	v_add_u32_e32 v65, 0xb0000, v64
	global_load_dword v77, v65, s[12:13]
	v_add_u32_e32 v65, 0xc0000, v64
	global_load_dword v78, v65, s[12:13]
	v_add_u32_e32 v65, 0xd0000, v64
	global_load_dword v79, v65, s[12:13]
	v_add_u32_e32 v65, 0xe0000, v64
	global_load_dword v80, v65, s[12:13]
	v_add_u32_e32 v65, 0xf0000, v64
	global_load_dword v81, v65, s[12:13]
.Lmy_tab_done:
	v_bfe_u32 v19, v17, 4, 2
	v_and_b32_e32 v18, 15, v17
	v_lshlrev_b32_e32 v21, 4, v19
	v_lshlrev_b32_e32 v17, 2, v17
	s_and_b32 s11, s7, 3
	v_lshl_or_b32 v239, s6, 6, v18
	v_lshl_or_b32 v18, v18, 6, v21
	s_lshl_b32 s6, s6, 13
	v_and_b32_e32 v17, 32, v17
	v_bitop3_b32 v240, v18, s6, v17 bitop3:0xde
	s_lshl_b32 s6, s11, 12
	v_bitop3_b32 v241, v18, s6, v17 bitop3:0xde
	v_readlane_b32 s6, v250, 7
	v_readlane_b32 s7, v250, 8
	s_lshl_b64 s[6:7], s[6:7], 2
	s_waitcnt lgkmcnt(0)
	s_add_u32 s4, s4, s6
	s_addc_u32 s5, s5, s7
	s_add_u32 s62, s70, 0x800000
	s_addc_u32 s63, s71, 0
	v_lshl_add_u64 v[2:3], v[2:3], 0, s[52:53]
	s_add_i32 m0, s34, 0x18000
	v_readlane_b32 s12, v250, 42
	s_nop 0
	s_cmp_eq_u32 s12, 0
	s_cbranch_scc1 .Lmy_w2
	s_waitcnt vmcnt(18)
	s_branch .Lmy_wdone

; #define PG8_WAIT_V(n) asm volatile("s_waitcnt vmcnt(" #n ")" ::: "memory")
; #define PG8_BAR __builtin_amdgcn_s_barrier()
; #define PG8_STA(bufoff, gbase, ld) PG8_STAGE(bufoff, gbase, RA0 * (unsigned)(ld) + CC0, RA1 * (unsigned)(ld) + CC1)
; #define PG8_STB(bufoff, gbase, ld) PG8_STAGE(bufoff, gbase, RB0 * (unsigned)(ld) + CC0, RB1 * (unsigned)(ld) + CC1)
; __device__ __forceinline__ void epi_rstd(const float* ssq, int row0, int fq, float (&rs)[2][4]) {
;     ...
;             for (int j = 0; j < 4; ++j) part[ai][m][j] = ssq[(size_t)(4 * fq + j) * M + row0 + ai * 128 + m * 16];
; #pragma unroll
;     for (int ai = 0; ai < 2; ++ai)
; #pragma unroll
;         for (int m = 0; m < 4; ++m) { float t = (part[ai][m][0] + part[ai][m][1]) + (part[ai][m][2] + part[ai][m][3]); t += __shfl_xor(t, 16); t += __shfl_xor(t, 32); rs[ai][m] = __builtin_amdgcn_rsqf(t * (1.0f / 1024.0f) + EPS); }
; __device__ __forceinline__ void gemm_phase(LAS unsigned char* lds, const Sched& S, const Epi& E) {
;     ...
;     PG8_STB(PG8_SB(1, 0), cB + kstep, ldb); PG8_STA(PG8_SA(1, 0), cA + kstep, lda); PG8_STB(PG8_SB(1, 1), cB + hB + kstep, ldb);
;     PG8_WAIT_V(6); PG8_BAR; }
.Lmy_wdone:
	s_barrier
	global_load_lds_dwordx4 v[2:3], off
	v_lshl_add_u64 v[2:3], v[4:5], 0, s[52:53]
	s_add_i32 m0, s34, 0x1a000
	s_add_i32 s90, s34, 0x8000
	global_load_lds_dwordx4 v[2:3], off
	v_lshl_add_u64 v[2:3], v[10:11], 0, s[52:53]
	s_mov_b32 m0, s90
	s_add_i32 s73, s34, 0xa000
	global_load_lds_dwordx4 v[2:3], off
	v_lshl_add_u64 v[2:3], v[12:13], 0, s[52:53]
	s_mov_b32 m0, s73
	v_writelane_b32 v250, s4, 27
	global_load_lds_dwordx4 v[2:3], off
	v_lshl_add_u64 v[2:3], v[6:7], 0, s[52:53]
	s_add_i32 m0, s34, 0x1c000
	v_writelane_b32 v250, s5, 28
	global_load_lds_dwordx4 v[2:3], off
	v_lshl_add_u64 v[2:3], v[8:9], 0, s[52:53]
	s_add_i32 m0, s34, 0x1e000
	s_cmpk_lt_u32 s2, 0x100
	global_load_lds_dwordx4 v[2:3], off
	s_cselect_b64 s[4:5], -1, 0
	s_lshl_b32 s6, s11, 14
	v_writelane_b32 v250, s11, 29
	s_or_b32 s6, s6, 0xfff80000
	v_writelane_b32 v250, s6, 30
	s_lshl_b32 s82, s15, 3
	v_readlane_b32 s6, v250, 21
	v_readlane_b32 s7, v250, 22
	v_readlane_b32 s61, v250, 20
	s_waitcnt vmcnt(6)
	v_readlane_b32 s12, v250, 42
	s_nop 0
	s_cmp_eq_u32 s12, 0
	s_cbranch_scc1 .Lmy_red_skip
	v_add_f32_e32 v66, v66, v67
	v_add_f32_e32 v68, v68, v69
	v_add_f32_e32 v66, v66, v68
	v_add_f32_e32 v70, v70, v71
	v_add_f32_e32 v72, v72, v73
	v_add_f32_e32 v70, v70, v72
	v_add_f32_e32 v74, v74, v75
	v_add_f32_e32 v76, v76, v77
	v_add_f32_e32 v74, v74, v76
	v_add_f32_e32 v78, v78, v79
	v_add_f32_e32 v80, v80, v81
	v_add_f32_e32 v78, v78, v80
	v_add_f32_e32 v66, v66, v70
	v_add_f32_e32 v74, v74, v78
	v_add_f32_e32 v66, v66, v74
	v_fmamk_f32 v66, v66, 0x3a800000, v197
	v_rsq_f32_e32 v66, v66
	v_and_b32_e32 v65, 0xff, v195
	v_lshlrev_b32_e32 v65, 2, v65
	v_add_u32_e32 v65, 0x20800, v65
	ds_write_b32 v65, v66
	v_writelane_b32 v250, s95, 41
